# RMSNorm row loop: 64-lane sum butterflies via DPP adds and permlane swaps instead of 12 ds_bpermute round trips
# speedup vs baseline: 1.0036x; 1.0036x over previous
.LBB0_139:
	v_ashrrev_i32_e32 v67, 31, v66
	v_add_u32_e32 v62, s28, v66
	v_lshlrev_b64 v[18:19], 12, v[66:67]
	v_cmp_gt_i32_e64 s[0:1], s3, v62
	v_lshl_add_u64 v[18:19], v[56:57], 0, v[18:19]
	global_load_dwordx4 v[46:49], v[18:19], off
	global_load_dwordx4 v[38:41], v[18:19], off offset:1024
	global_load_dwordx4 v[22:25], v[18:19], off offset:3072
	global_load_dwordx4 v[30:33], v[18:19], off offset:2048
	v_cndmask_b32_e64 v68, v66, v62, s[0:1]
	v_ashrrev_i32_e32 v69, 31, v68
	v_lshlrev_b64 v[18:19], 12, v[68:69]
	v_lshl_add_u64 v[64:65], v[56:57], 0, v[18:19]
	global_load_dwordx4 v[42:45], v[64:65], off
	global_load_dwordx4 v[34:37], v[64:65], off offset:1024
	global_load_dwordx4 v[18:21], v[64:65], off offset:3072
	global_load_dwordx4 v[26:29], v[64:65], off offset:2048
	v_ashrrev_i32_e32 v53, 12, v66
	v_mul_hi_i32_i24_e32 v65, 0x6000, v53
	v_mul_i32_i24_e32 v64, 0x6000, v53
	v_lshl_add_u64 v[64:65], v[58:59], 0, v[64:65]
	v_add_co_u32_e32 v70, vcc, s12, v64
	global_load_dwordx4 v[82:85], v[64:65], off
	s_nop 0
	v_addc_co_u32_e32 v71, vcc, 0, v65, vcc
	global_load_dwordx4 v[72:75], v[70:71], off
	global_load_dwordx4 v[198:201], v[70:71], off offset:1024
	global_load_dwordx4 v[202:205], v[70:71], off offset:2048
	global_load_dwordx4 v[206:209], v[70:71], off offset:3072
	global_load_dwordx4 v[210:213], v[64:65], off offset:1024
	global_load_dwordx4 v[214:217], v[64:65], off offset:2048
	global_load_dwordx4 v[218:221], v[64:65], off offset:3072
	v_ashrrev_i32_e32 v86, 12, v68
	v_mul_hi_i32_i24_e32 v87, 0x6000, v86
	v_mul_i32_i24_e32 v86, 0x6000, v86
	v_lshl_add_u64 v[86:87], v[58:59], 0, v[86:87]
	global_load_dwordx4 v[222:225], v[86:87], off
	global_load_dwordx4 v[226:229], v[86:87], off offset:1024
	global_load_dwordx4 v[230:233], v[86:87], off offset:2048
	global_load_dwordx4 v[234:237], v[86:87], off offset:3072
	v_add_co_u32_e32 v86, vcc, 0x1000, v86
	s_nop 1
	v_addc_co_u32_e32 v87, vcc, 0, v87, vcc
	global_load_dwordx4 v[238:241], v[86:87], off
	global_load_dwordx4 v[242:245], v[86:87], off offset:1024
	global_load_dwordx4 v[246:249], v[86:87], off offset:2048
	global_load_dwordx4 v[250:253], v[86:87], off offset:3072
	v_lshlrev_b64 v[66:67], 11, v[66:67]
	v_ashrrev_i32_e32 v68, 12, v68
	s_waitcnt vmcnt(23)
	v_pk_mul_f32 v[70:71], v[48:49], v[48:49]
	v_pk_mul_f32 v[86:87], v[46:47], v[46:47]
	s_waitcnt vmcnt(22)
	v_pk_mul_f32 v[88:89], v[40:41], v[40:41]
	v_pk_mul_f32 v[90:91], v[38:39], v[38:39]
	v_pk_mov_b32 v[96:97], v[86:87], v[70:71] op_sel:[1,0]
	v_mov_b32_e32 v87, v71
	v_pk_mov_b32 v[70:71], v[90:91], v[88:89] op_sel:[1,0]
	v_mov_b32_e32 v91, v89
	s_waitcnt vmcnt(20)
	v_mul_f32_e32 v92, v31, v31
	v_mul_f32_e32 v94, v33, v33
	v_pk_add_f32 v[86:87], v[96:97], v[86:87]
	v_pk_add_f32 v[70:71], v[70:71], v[90:91]
	v_mul_f32_e32 v53, v22, v22
	v_mul_f32_e32 v63, v23, v23
	v_mul_f32_e32 v69, v24, v24
	v_mul_f32_e32 v100, v25, v25
	v_pk_fma_f32 v[88:89], v[30:31], v[30:31], v[92:93] op_sel_hi:[1,1,0]
	v_pk_fma_f32 v[92:93], v[32:33], v[32:33], v[94:95] op_sel_hi:[1,1,0]
	s_waitcnt vmcnt(19)
	v_pk_mul_f32 v[94:95], v[44:45], v[44:45]
	v_pk_mul_f32 v[96:97], v[42:43], v[42:43]
	s_waitcnt vmcnt(18)
	v_pk_mul_f32 v[90:91], v[36:37], v[36:37]
	v_pk_mul_f32 v[98:99], v[34:35], v[34:35]
	v_pk_add_f32 v[86:87], v[86:87], v[86:87] op_sel:[0,1] op_sel_hi:[1,0]
	v_pk_add_f32 v[70:71], v[70:71], v[70:71] op_sel:[0,1] op_sel_hi:[1,0]
	v_mov_b32_e32 v89, v69
	v_mov_b32_e32 v93, v100
	v_pk_mov_b32 v[104:105], v[96:97], v[94:95] op_sel:[1,0]
	v_mov_b32_e32 v97, v95
	v_pk_mov_b32 v[94:95], v[98:99], v[90:91] op_sel:[1,0]
	v_mov_b32_e32 v99, v91
	v_mov_b32_e32 v87, v53
	v_mov_b32_e32 v71, v63
	s_waitcnt vmcnt(17)
	v_mul_f32_e32 v101, v19, v19
	v_mul_f32_e32 v103, v20, v20
	s_waitcnt vmcnt(16)
	v_mul_f32_e32 v100, v27, v27
	v_mul_f32_e32 v102, v29, v29
	v_pk_add_f32 v[88:89], v[88:89], v[92:93]
	v_pk_add_f32 v[96:97], v[104:105], v[96:97]
	v_pk_add_f32 v[94:95], v[94:95], v[98:99]
	v_pk_add_f32 v[70:71], v[86:87], v[70:71]
	v_mul_f32_e32 v69, v18, v18
	v_mul_f32_e32 v106, v21, v21
	v_pk_fma_f32 v[90:91], v[26:27], v[26:27], v[100:101] op_sel_hi:[1,1,0]
	v_pk_fma_f32 v[92:93], v[28:29], v[28:29], v[102:103] op_sel_hi:[1,1,0]
	v_pk_add_f32 v[86:87], v[96:97], v[96:97] op_sel:[0,1] op_sel_hi:[1,0]
	v_pk_add_f32 v[94:95], v[94:95], v[94:95] op_sel:[0,1] op_sel_hi:[1,0]
	v_pk_add_f32 v[70:71], v[70:71], v[88:89]
	v_mov_b32_e32 v91, v103
	v_mov_b32_e32 v93, v106
	v_mov_b32_e32 v87, v69
	v_mov_b32_e32 v95, v101
	v_add_f32_e32 v53, v70, v71
	v_pk_add_f32 v[90:91], v[90:91], v[92:93]
	v_pk_add_f32 v[70:71], v[86:87], v[94:95]
	v_pk_add_f32 v[70:71], v[70:71], v[90:91]
	v_add_f32_e32 v102, v70, v71
	s_nop 1
	v_add_f32_dpp v53, v53, v53 quad_perm:[1,0,3,2] row_mask:0xf bank_mask:0xf
	v_add_f32_dpp v102, v102, v102 quad_perm:[1,0,3,2] row_mask:0xf bank_mask:0xf
	v_ashrrev_i32_e32 v63, 31, v62
	v_add_f32_dpp v53, v53, v53 quad_perm:[2,3,0,1] row_mask:0xf bank_mask:0xf
	v_add_f32_dpp v102, v102, v102 quad_perm:[2,3,0,1] row_mask:0xf bank_mask:0xf
	v_lshl_add_u64 v[70:71], v[60:61], 0, v[66:67]
	v_add_f32_dpp v53, v53, v53 row_half_mirror row_mask:0xf bank_mask:0xf
	v_add_f32_dpp v102, v102, v102 row_half_mirror row_mask:0xf bank_mask:0xf
	v_lshlrev_b64 v[66:67], 11, v[62:63]
	v_add_f32_dpp v53, v53, v53 row_mirror row_mask:0xf bank_mask:0xf
	v_add_f32_dpp v102, v102, v102 row_mirror row_mask:0xf bank_mask:0xf
	v_mul_hi_i32_i24_e32 v69, 0x6000, v68
	v_mov_b32_e32 v100, v53
	v_mov_b32_e32 v101, v102
	v_mul_i32_i24_e32 v68, 0x6000, v68
	s_nop 1
	v_permlane16_swap_b32_e32 v53, v100
	v_permlane16_swap_b32_e32 v102, v101
	v_lshl_add_u64 v[66:67], v[60:61], 0, v[66:67]
	v_lshl_add_u64 v[68:69], v[58:59], 0, v[68:69]
	v_add_f32_e32 v53, v53, v100
	v_add_f32_e32 v102, v102, v101
	v_mov_b32_e32 v100, v53
	v_mov_b32_e32 v101, v102
	s_nop 1
	v_permlane32_swap_b32_e32 v53, v100
	v_permlane32_swap_b32_e32 v102, v101
	s_waitcnt vmcnt(0)
	v_pk_add_f32 v[86:87], v[74:75], 1.0 op_sel_hi:[1,0]
	v_add_f32_e32 v53, v53, v100
	v_fmamk_f32 v53, v53, 0x3a800000, v51
	v_rsq_f32_e32 v74, v53
	v_pk_add_f32 v[88:89], v[72:73], 1.0 op_sel_hi:[1,0]
	v_add_f32_e32 v53, v102, v101
	v_fmamk_f32 v53, v53, 0x3a800000, v51
	v_rsq_f32_e32 v72, v53
	v_pk_mul_f32 v[48:49], v[48:49], v[74:75] op_sel_hi:[1,0]
	v_pk_mul_f32 v[46:47], v[46:47], v[74:75] op_sel_hi:[1,0]
	v_pk_mul_f32 v[48:49], v[4:5], v[48:49]
	v_pk_mul_f32 v[46:47], v[2:3], v[46:47]
	v_pk_fma_f32 v[48:49], v[86:87], v[48:49], v[84:85]
	v_pk_fma_f32 v[46:47], v[88:89], v[46:47], v[82:83]
	v_mov_b32_e32 v73, v72
	v_cvt_pk_bf16_f32 v46, v46, v47
	v_cvt_pk_bf16_f32 v47, v48, v49
	global_store_dwordx2 v[70:71], v[46:47], off
	s_and_saveexec_b64 s[10:11], s[0:1]
	s_cbranch_execz .LBB0_141
	v_add_co_u32_e32 v86, vcc, 0x1000, v68
	v_pk_mul_f32 v[42:43], v[42:43], v[72:73]
	s_nop 0
	v_addc_co_u32_e32 v87, vcc, 0, v69, vcc
	v_pk_mov_b32 v[46:47], v[238:239], v[238:239] op_sel:[0,1]
	v_pk_mov_b32 v[48:49], v[240:241], v[240:241] op_sel:[0,1]
	v_pk_mov_b32 v[82:83], v[222:223], v[222:223] op_sel:[0,1]
	v_pk_mov_b32 v[84:85], v[224:225], v[224:225] op_sel:[0,1]
	v_mov_b32_e32 v86, v72
	v_mov_b32_e32 v87, v72
	v_pk_mul_f32 v[44:45], v[44:45], v[86:87]
	v_pk_mul_f32 v[42:43], v[2:3], v[42:43]
	v_pk_mul_f32 v[44:45], v[4:5], v[44:45]
	v_pk_add_f32 v[48:49], v[48:49], 1.0 op_sel_hi:[1,0]
	v_pk_add_f32 v[46:47], v[46:47], 1.0 op_sel_hi:[1,0]
	v_pk_fma_f32 v[44:45], v[44:45], v[48:49], v[84:85]
	v_pk_fma_f32 v[42:43], v[42:43], v[46:47], v[82:83]
	s_nop 0
	v_cvt_pk_bf16_f32 v42, v42, v43
	v_cvt_pk_bf16_f32 v43, v44, v45
	global_store_dwordx2 v[66:67], v[42:43], off
